# EpiResid epilogue: 16 residual loads hoisted above the barrier, single wait
# speedup vs baseline: 1.0041x; 1.0041x over previous
; #define PG8_STAGE(bufoff, gbase, voff) do { _Pragma("unroll") for (int _i = 0; _i < 2; ++_i) \
;         __builtin_amdgcn_global_load_lds((const unsigned*)((const char*)(gbase) + (voff)[_i]), (PG8_LAS unsigned*)(lds + (bufoff) + ldsw + _i * 8192), 16, 0, 0); } while (0)
; #define PG8_LDA(dst, b, h) do { _Pragma("unroll") for (int m = 0; m < 4; ++m) _Pragma("unroll") for (int k = 0; k < 2; ++k) dst[m][k] = *(const PG8_LAS bf16x8*)(lds + PG8_SA(b, h) + aoff + m * 2048 + k * 1024); } while (0)
; #define PG8_LDB(dst, b, h) do { _Pragma("unroll") for (int n = 0; n < 2; ++n) _Pragma("unroll") for (int k = 0; k < 2; ++k) dst[n][k] = *(const PG8_LAS bf16x8*)(lds + PG8_SB(b, h) + boff + n * 2048 + k * 1024); } while (0)
; #define PG8_MMA(ai, bj, At, Bt) do { __builtin_amdgcn_s_setprio(1); _Pragma("unroll") for (int m = 0; m < 4; ++m) _Pragma("unroll") for (int n = 0; n < 2; ++n) _Pragma("unroll") for (int k = 0; k < 2; ++k) \
;         acc[ai][bj][m][n] = __builtin_amdgcn_mfma_f32_16x16x32_bf16(Bt[n][k], At[m][k], acc[ai][bj][m][n], 0, 0, 0); __builtin_amdgcn_s_setprio(0); } while (0)
; #define PG8_WAIT_V(n) asm volatile("s_waitcnt vmcnt(" #n ")" ::: "memory")
; #define PG8_WAIT_L(n) asm volatile("s_waitcnt lgkmcnt(" #n ")" ::: "memory")
; #define PG8_BAR __builtin_amdgcn_s_barrier()
; #define PG8_SCHED __builtin_amdgcn_sched_barrier(0)
; template <class Epi, class Sched, bool ALIGN_EPI = false, bool SP2 = false>
; __device__ __forceinline__ void gemm_phase(PG8_LAS unsigned char* lds, const Gemm g, const Sched& S, const Epi& E) {
;     ...
;         for (int t = 0; t < nt; t += 2) {
;             const bool last = (t == nt - 2);
;             const char* a1 = cA + (size_t)(t + 1) * kstep;
;             const char* a2 = last ? nA : cA + (size_t)(t + 2) * kstep; const char* b2 = last ? nB : cB + (size_t)(t + 2) * kstep;
;             const char* a3 = a2 + kstep; const char* b3 = b2 + kstep;
;             if (last && has_next) S.a_ready(nxt);
;             if constexpr (SP2) {
;             PG8_LDB(B0, 0, 0); PG8_LDB(B1, 0, 1); PG8_SCHED; PG8_LDA(At, 0, 0); PG8_STAGE(PG8_SA(1, 1), a1 + hstep, voffA);
;             PG8_WAIT_V(8); PG8_WAIT_L(0); PG8_BAR; PG8_MMA(0, 0, At, B0); PG8_MMA(0, 1, At, B1); PG8_BAR; PG8_SCHED;
;             PG8_LDA(At, 0, 1); PG8_STAGE(PG8_SB(0, 0), b2, voffB); PG8_STAGE(PG8_SB(0, 1), b2 + hstep, voffB); PG8_STAGE(PG8_SA(0, 0), a2, voffA);
.LBB0_218:
	s_add_i32 vcc_lo, s46, 2
	s_add_u32 s68, s44, 0x80
	s_addc_u32 s47, s45, 0
	s_add_i32 vcc_hi, 0, 0x10000
	s_cmp_eq_u32 s15, s46
	s_cselect_b32 s47, s83, s47
	s_cselect_b32 s46, s82, s68
	v_add_u32_e32 v146, vcc_hi, v149
	s_cselect_b32 s69, s85, s87
	s_cselect_b32 s68, s84, s86
	s_add_i32 s96, 0, 0x14000
	ds_read_b128 v[138:141], v146
	ds_read_b128 v[142:145], v146 offset:1024
	ds_read_b128 v[156:159], v146 offset:2048
	ds_read_b128 v[160:163], v146 offset:3072
	v_add_u32_e32 v146, s96, v149
	ds_read_b128 v[164:167], v146
	ds_read_b128 v[168:171], v146 offset:1024
	ds_read_b128 v[172:175], v146 offset:2048
	ds_read_b128 v[192:195], v146 offset:3072
	v_lshl_add_u64 v[146:147], s[44:45], 0, v[134:135]
	s_add_i32 m0, s54, 0xc000
	ds_read_b128 v[196:199], v151
	ds_read_b128 v[200:203], v151 offset:1024
	ds_read_b128 v[204:207], v151 offset:2048
	ds_read_b128 v[208:211], v151 offset:3072
	ds_read_b128 v[212:215], v151 offset:4096
	ds_read_b128 v[216:219], v151 offset:5120
	ds_read_b128 v[220:223], v151 offset:6144
	ds_read_b128 v[224:227], v151 offset:7168
	global_load_lds_dwordx4 v[146:147], off
	v_lshl_add_u64 v[146:147], s[44:45], 0, v[136:137]
	s_add_i32 m0, s54, 0xe000
	s_nop 0
	global_load_lds_dwordx4 v[146:147], off
	s_waitcnt vmcnt(8)
	s_waitcnt lgkmcnt(0)
	s_barrier
	s_setprio 1
	s_waitcnt lgkmcnt(0)
	v_mfma_f32_16x16x32_bf16 v[124:127], v[138:141], v[196:199], v[124:127]
	v_mfma_f32_16x16x32_bf16 v[120:123], v[156:159], v[196:199], v[120:123]
	v_mfma_f32_16x16x32_bf16 v[108:111], v[138:141], v[204:207], v[108:111]
	v_mfma_f32_16x16x32_bf16 v[104:107], v[156:159], v[204:207], v[104:107]
	v_mfma_f32_16x16x32_bf16 v[92:95], v[138:141], v[212:215], v[92:95]
	v_mfma_f32_16x16x32_bf16 v[88:91], v[156:159], v[212:215], v[88:91]
	v_mfma_f32_16x16x32_bf16 v[76:79], v[138:141], v[220:223], v[76:79]
	v_mfma_f32_16x16x32_bf16 v[72:75], v[156:159], v[220:223], v[72:75]
	v_mfma_f32_16x16x32_bf16 v[124:127], v[142:145], v[200:203], v[124:127]
	v_mfma_f32_16x16x32_bf16 v[120:123], v[160:163], v[200:203], v[120:123]
	v_mfma_f32_16x16x32_bf16 v[108:111], v[142:145], v[208:211], v[108:111]
	v_mfma_f32_16x16x32_bf16 v[104:107], v[160:163], v[208:211], v[104:107]
	v_mfma_f32_16x16x32_bf16 v[92:95], v[142:145], v[216:219], v[92:95]
	v_mfma_f32_16x16x32_bf16 v[88:91], v[160:163], v[216:219], v[88:91]
	v_mfma_f32_16x16x32_bf16 v[76:79], v[142:145], v[224:227], v[76:79]
	v_mfma_f32_16x16x32_bf16 v[72:75], v[160:163], v[224:227], v[72:75]
	s_setprio 0
	s_setprio 1
	v_mfma_f32_16x16x32_bf16 v[116:119], v[164:167], v[196:199], v[116:119]
	v_mfma_f32_16x16x32_bf16 v[112:115], v[172:175], v[196:199], v[112:115]
	v_mfma_f32_16x16x32_bf16 v[100:103], v[164:167], v[204:207], v[100:103]
	v_mfma_f32_16x16x32_bf16 v[96:99], v[172:175], v[204:207], v[96:99]
	v_mfma_f32_16x16x32_bf16 v[84:87], v[164:167], v[212:215], v[84:87]
	v_mfma_f32_16x16x32_bf16 v[80:83], v[172:175], v[212:215], v[80:83]
	v_mfma_f32_16x16x32_bf16 v[68:71], v[164:167], v[220:223], v[68:71]
	v_mfma_f32_16x16x32_bf16 v[64:67], v[172:175], v[220:223], v[64:67]
	v_mfma_f32_16x16x32_bf16 v[116:119], v[168:171], v[200:203], v[116:119]
	v_mfma_f32_16x16x32_bf16 v[112:115], v[192:195], v[200:203], v[112:115]
	v_mfma_f32_16x16x32_bf16 v[100:103], v[168:171], v[208:211], v[100:103]
	v_mfma_f32_16x16x32_bf16 v[96:99], v[192:195], v[208:211], v[96:99]
	v_mfma_f32_16x16x32_bf16 v[84:87], v[168:171], v[216:219], v[84:87]
	v_mfma_f32_16x16x32_bf16 v[80:83], v[192:195], v[216:219], v[80:83]
	v_mfma_f32_16x16x32_bf16 v[68:71], v[168:171], v[224:227], v[68:71]
	v_mfma_f32_16x16x32_bf16 v[64:67], v[192:195], v[224:227], v[64:67]
	s_setprio 0
	s_barrier
	s_add_i32 vcc_hi, vcc_hi, s63
	v_lshl_add_u64 v[146:147], s[68:69], 0, v[152:153]
	s_mov_b32 m0, vcc_hi
	ds_read_b128 v[196:199], v151 offset:16384
	ds_read_b128 v[200:203], v151 offset:17408
	ds_read_b128 v[204:207], v151 offset:18432
	ds_read_b128 v[208:211], v151 offset:19456
	ds_read_b128 v[212:215], v151 offset:20480
	ds_read_b128 v[216:219], v151 offset:21504
	ds_read_b128 v[220:223], v151 offset:22528
	ds_read_b128 v[224:227], v151 offset:23552
	global_load_lds_dwordx4 v[146:147], off
	s_add_i32 m0, vcc_hi, 0x2000
	v_lshl_add_u64 v[182:183], s[68:69], 0, v[128:129]
	s_add_u32 s68, s68, s48
	s_addc_u32 s69, s69, 0
	s_add_i32 s96, s96, s63
	global_load_lds_dwordx4 v[182:183], off
	v_lshl_add_u64 v[184:185], s[68:69], 0, v[152:153]
	s_mov_b32 m0, s96
	v_lshl_add_u64 v[188:189], s[68:69], 0, v[128:129]
	global_load_lds_dwordx4 v[184:185], off
	s_add_i32 m0, s96, 0x2000
	v_lshl_add_u64 v[190:191], s[46:47], 0, v[132:133]
	global_load_lds_dwordx4 v[188:189], off
	s_mov_b32 m0, s54
	v_lshl_add_u64 v[228:229], s[46:47], 0, v[130:131]
	global_load_lds_dwordx4 v[190:191], off
	s_mov_b32 m0, s55
	s_nop 0
	global_load_lds_dwordx4 v[228:229], off
	s_waitcnt vmcnt(8)
	s_waitcnt lgkmcnt(0)
	s_barrier
; #define PG8_STAGE(bufoff, gbase, voff) do { _Pragma("unroll") for (int _i = 0; _i < 2; ++_i) \
;         __builtin_amdgcn_global_load_lds((const unsigned*)((const char*)(gbase) + (voff)[_i]), (PG8_LAS unsigned*)(lds + (bufoff) + ldsw + _i * 8192), 16, 0, 0); } while (0)
; #define PG8_LDA(dst, b, h) do { _Pragma("unroll") for (int m = 0; m < 4; ++m) _Pragma("unroll") for (int k = 0; k < 2; ++k) dst[m][k] = *(const PG8_LAS bf16x8*)(lds + PG8_SA(b, h) + aoff + m * 2048 + k * 1024); } while (0)
; #define PG8_LDB(dst, b, h) do { _Pragma("unroll") for (int n = 0; n < 2; ++n) _Pragma("unroll") for (int k = 0; k < 2; ++k) dst[n][k] = *(const PG8_LAS bf16x8*)(lds + PG8_SB(b, h) + boff + n * 2048 + k * 1024); } while (0)
; #define PG8_MMA(ai, bj, At, Bt) do { __builtin_amdgcn_s_setprio(1); _Pragma("unroll") for (int m = 0; m < 4; ++m) _Pragma("unroll") for (int n = 0; n < 2; ++n) _Pragma("unroll") for (int k = 0; k < 2; ++k) \
;         acc[ai][bj][m][n] = __builtin_amdgcn_mfma_f32_16x16x32_bf16(Bt[n][k], At[m][k], acc[ai][bj][m][n], 0, 0, 0); __builtin_amdgcn_s_setprio(0); } while (0)
; #define PG8_WAIT_V(n) asm volatile("s_waitcnt vmcnt(" #n ")" ::: "memory")
; #define PG8_WAIT_L(n) asm volatile("s_waitcnt lgkmcnt(" #n ")" ::: "memory")
; #define PG8_BAR __builtin_amdgcn_s_barrier()
; #define PG8_SCHED __builtin_amdgcn_sched_barrier(0)
; template <class Epi, class Sched, bool ALIGN_EPI = false, bool SP2 = false>
; __device__ __forceinline__ void gemm_phase(PG8_LAS unsigned char* lds, const Gemm g, const Sched& S, const Epi& E) {
;     ...
;             PG8_WAIT_V(8); PG8_WAIT_L(0); PG8_BAR; PG8_MMA(1, 0, At, B0); PG8_MMA(1, 1, At, B1); PG8_BAR; PG8_SCHED;
;             PG8_LDB(B0, 1, 0); PG8_LDB(B1, 1, 1); PG8_SCHED; PG8_LDA(At, 1, 0); PG8_STAGE(PG8_SA(0, 1), a2 + hstep, voffA);
;             PG8_WAIT_V(8); PG8_WAIT_L(0); PG8_BAR; PG8_MMA(0, 0, At, B0); PG8_MMA(0, 1, At, B1); PG8_BAR; PG8_SCHED;
	s_setprio 1
	s_waitcnt lgkmcnt(0)
	v_mfma_f32_16x16x32_bf16 v[60:63], v[138:141], v[196:199], v[60:63]
	v_mfma_f32_16x16x32_bf16 v[56:59], v[156:159], v[196:199], v[56:59]
	v_mfma_f32_16x16x32_bf16 v[44:47], v[138:141], v[204:207], v[44:47]
	v_mfma_f32_16x16x32_bf16 v[40:43], v[156:159], v[204:207], v[40:43]
	v_mfma_f32_16x16x32_bf16 v[28:31], v[138:141], v[212:215], v[28:31]
	v_mfma_f32_16x16x32_bf16 v[24:27], v[156:159], v[212:215], v[24:27]
	v_mfma_f32_16x16x32_bf16 v[12:15], v[138:141], v[220:223], v[12:15]
	v_mfma_f32_16x16x32_bf16 v[8:11], v[156:159], v[220:223], v[8:11]
	v_mfma_f32_16x16x32_bf16 v[60:63], v[142:145], v[200:203], v[60:63]
	v_mfma_f32_16x16x32_bf16 v[56:59], v[160:163], v[200:203], v[56:59]
	v_mfma_f32_16x16x32_bf16 v[44:47], v[142:145], v[208:211], v[44:47]
	v_mfma_f32_16x16x32_bf16 v[40:43], v[160:163], v[208:211], v[40:43]
	v_mfma_f32_16x16x32_bf16 v[28:31], v[142:145], v[216:219], v[28:31]
	v_mfma_f32_16x16x32_bf16 v[24:27], v[160:163], v[216:219], v[24:27]
	v_mfma_f32_16x16x32_bf16 v[12:15], v[142:145], v[224:227], v[12:15]
	v_mfma_f32_16x16x32_bf16 v[8:11], v[160:163], v[224:227], v[8:11]
	s_setprio 0
	s_setprio 1
	v_mfma_f32_16x16x32_bf16 v[52:55], v[164:167], v[196:199], v[52:55]
	v_mfma_f32_16x16x32_bf16 v[48:51], v[172:175], v[196:199], v[48:51]
	v_mfma_f32_16x16x32_bf16 v[36:39], v[164:167], v[204:207], v[36:39]
	v_mfma_f32_16x16x32_bf16 v[32:35], v[172:175], v[204:207], v[32:35]
	v_mfma_f32_16x16x32_bf16 v[20:23], v[164:167], v[212:215], v[20:23]
	v_mfma_f32_16x16x32_bf16 v[16:19], v[172:175], v[212:215], v[16:19]
	v_mfma_f32_16x16x32_bf16 v[4:7], v[164:167], v[220:223], v[4:7]
	v_mfma_f32_16x16x32_bf16 v[0:3], v[172:175], v[220:223], v[0:3]
	v_mfma_f32_16x16x32_bf16 v[52:55], v[168:171], v[200:203], v[52:55]
	v_mfma_f32_16x16x32_bf16 v[48:51], v[192:195], v[200:203], v[48:51]
	v_mfma_f32_16x16x32_bf16 v[36:39], v[168:171], v[208:211], v[36:39]
	v_mfma_f32_16x16x32_bf16 v[32:35], v[192:195], v[208:211], v[32:35]
	v_mfma_f32_16x16x32_bf16 v[20:23], v[168:171], v[216:219], v[20:23]
	v_mfma_f32_16x16x32_bf16 v[16:19], v[192:195], v[216:219], v[16:19]
	v_mfma_f32_16x16x32_bf16 v[4:7], v[168:171], v[224:227], v[4:7]
	v_mfma_f32_16x16x32_bf16 v[0:3], v[192:195], v[224:227], v[0:3]
	s_setprio 0
	s_barrier
	v_add_u32_e32 v155, s93, v149
	s_add_i32 s68, 0, 0x1c000
	ds_read_b128 v[138:141], v155
	ds_read_b128 v[142:145], v155 offset:1024
	ds_read_b128 v[156:159], v155 offset:2048
	ds_read_b128 v[160:163], v155 offset:3072
	v_add_u32_e32 v155, s68, v149
	ds_read_b128 v[164:167], v155
	ds_read_b128 v[168:171], v155 offset:1024
	ds_read_b128 v[172:175], v155 offset:2048
	ds_read_b128 v[192:195], v155 offset:3072
	s_add_u32 s46, s46, s48
	s_addc_u32 s47, s47, 0
	s_mov_b32 m0, s34
	v_lshl_add_u64 v[230:231], s[46:47], 0, v[132:133]
	ds_read_b128 v[196:199], v151 offset:32768
	ds_read_b128 v[200:203], v151 offset:33792
	ds_read_b128 v[204:207], v151 offset:34816
	ds_read_b128 v[208:211], v151 offset:35840
	ds_read_b128 v[212:215], v151 offset:36864
	ds_read_b128 v[216:219], v151 offset:37888
	ds_read_b128 v[220:223], v151 offset:38912
	ds_read_b128 v[224:227], v151 offset:39936
	global_load_lds_dwordx4 v[230:231], off
	v_lshl_add_u64 v[230:231], s[46:47], 0, v[130:131]
	s_mov_b32 m0, s95
	s_nop 0
	global_load_lds_dwordx4 v[230:231], off
	s_waitcnt vmcnt(8)
	s_waitcnt lgkmcnt(0)
	s_barrier
	s_setprio 1
	s_waitcnt lgkmcnt(0)
	v_mfma_f32_16x16x32_bf16 v[124:127], v[138:141], v[196:199], v[124:127]
	v_mfma_f32_16x16x32_bf16 v[120:123], v[156:159], v[196:199], v[120:123]
	v_mfma_f32_16x16x32_bf16 v[108:111], v[138:141], v[204:207], v[108:111]
	v_mfma_f32_16x16x32_bf16 v[104:107], v[156:159], v[204:207], v[104:107]
	v_mfma_f32_16x16x32_bf16 v[92:95], v[138:141], v[212:215], v[92:95]
	v_mfma_f32_16x16x32_bf16 v[88:91], v[156:159], v[212:215], v[88:91]
	v_mfma_f32_16x16x32_bf16 v[76:79], v[138:141], v[220:223], v[76:79]
	v_mfma_f32_16x16x32_bf16 v[72:75], v[156:159], v[220:223], v[72:75]
	v_mfma_f32_16x16x32_bf16 v[124:127], v[142:145], v[200:203], v[124:127]
	v_mfma_f32_16x16x32_bf16 v[120:123], v[160:163], v[200:203], v[120:123]
	v_mfma_f32_16x16x32_bf16 v[108:111], v[142:145], v[208:211], v[108:111]
	v_mfma_f32_16x16x32_bf16 v[104:107], v[160:163], v[208:211], v[104:107]
	v_mfma_f32_16x16x32_bf16 v[92:95], v[142:145], v[216:219], v[92:95]
	v_mfma_f32_16x16x32_bf16 v[88:91], v[160:163], v[216:219], v[88:91]
	v_mfma_f32_16x16x32_bf16 v[76:79], v[142:145], v[224:227], v[76:79]
	v_mfma_f32_16x16x32_bf16 v[72:75], v[160:163], v[224:227], v[72:75]
	s_setprio 0
	s_setprio 1
	v_mfma_f32_16x16x32_bf16 v[116:119], v[164:167], v[196:199], v[116:119]
	v_mfma_f32_16x16x32_bf16 v[112:115], v[172:175], v[196:199], v[112:115]
	v_mfma_f32_16x16x32_bf16 v[100:103], v[164:167], v[204:207], v[100:103]
	v_mfma_f32_16x16x32_bf16 v[96:99], v[172:175], v[204:207], v[96:99]
	v_mfma_f32_16x16x32_bf16 v[84:87], v[164:167], v[212:215], v[84:87]
	v_mfma_f32_16x16x32_bf16 v[80:83], v[172:175], v[212:215], v[80:83]
	v_mfma_f32_16x16x32_bf16 v[68:71], v[164:167], v[220:223], v[68:71]
	v_mfma_f32_16x16x32_bf16 v[64:67], v[172:175], v[220:223], v[64:67]
	v_mfma_f32_16x16x32_bf16 v[116:119], v[168:171], v[200:203], v[116:119]
	v_mfma_f32_16x16x32_bf16 v[112:115], v[192:195], v[200:203], v[112:115]
	v_mfma_f32_16x16x32_bf16 v[100:103], v[168:171], v[208:211], v[100:103]
	v_mfma_f32_16x16x32_bf16 v[96:99], v[192:195], v[208:211], v[96:99]
	v_mfma_f32_16x16x32_bf16 v[84:87], v[168:171], v[216:219], v[84:87]
	v_mfma_f32_16x16x32_bf16 v[80:83], v[192:195], v[216:219], v[80:83]
	v_mfma_f32_16x16x32_bf16 v[68:71], v[168:171], v[224:227], v[68:71]
	v_mfma_f32_16x16x32_bf16 v[64:67], v[192:195], v[224:227], v[64:67]
	s_setprio 0
	s_barrier
;     __device__ __forceinline__ void operator()(const f32x4 (&acc)[2][2][4][2], const Unit& u, int wr, int wc, int fr, int fq) const {
;     ...
;                 for (int bj = 0; bj < 2; ++bj) { const size_t off = (size_t)row * 2048 + col0 + bj * HALF;
;                     f32x4 b0, b1;
;                     if (base32) { b0 = *(const f32x4*)(base32 + off); b1 = *(const f32x4*)(base32 + off + 4); }
;                     else { const u32x4 bw = *(const u32x4*)(xb + off);
; template <class Epi, class Sched, bool ALIGN_EPI = false, bool SP2 = false>
; __device__ __forceinline__ void gemm_phase(PG8_LAS unsigned char* lds, const Gemm g, const Sched& S, const Epi& E) {
;     ...
;             PG8_LDA(At, 1, 1); PG8_STAGE(PG8_SB(1, 0), b3, voffB); PG8_STAGE(PG8_SB(1, 1), b3 + hstep, voffB); PG8_STAGE(PG8_SA(1, 0), a3, voffA);
;             PG8_WAIT_V(8); PG8_WAIT_L(0); PG8_BAR; PG8_MMA(1, 0, At, B0); PG8_MMA(1, 1, At, B1); PG8_BAR; PG8_SCHED;
;             } else {
;             PG8_LDB(B0, 0, 0); PG8_SCHED; PG8_LDA(At, 0, 0); PG8_STAGE(PG8_SA(1, 1), a1 + hstep, voffA);
;             PG8_WAIT_L(8); PG8_BAR; PG8_WAIT_L(0); PG8_MMA(0, 0, At, B0); PG8_BAR; PG8_SCHED;
;             PG8_LDB(B1, 0, 1); PG8_STAGE(PG8_SB(0, 0), b2, voffB);
;             PG8_BAR; PG8_WAIT_L(0); PG8_MMA(0, 1, At, B1); PG8_BAR;
;             PG8_LDA(At, 0, 1); PG8_STAGE(PG8_SA(0, 0), a2, voffA);
;             PG8_BAR; PG8_WAIT_L(0); PG8_MMA(1, 0, At, B0); PG8_BAR; PG8_SCHED;
;             PG8_STAGE(PG8_SB(0, 1), b2 + hstep, voffB);
;             PG8_WAIT_V(6); PG8_BAR; PG8_MMA(1, 1, At, B1); PG8_BAR;
;             PG8_LDB(B0, 1, 0); PG8_SCHED; PG8_LDA(At, 1, 0); PG8_STAGE(PG8_SA(0, 1), a2 + hstep, voffA);
;             PG8_WAIT_L(8); PG8_BAR; PG8_WAIT_L(0); PG8_MMA(0, 0, At, B0); PG8_BAR; PG8_SCHED;
;             PG8_LDB(B1, 1, 1); PG8_STAGE(PG8_SB(1, 0), b3, voffB);
;             PG8_BAR; PG8_WAIT_L(0); PG8_MMA(0, 1, At, B1); PG8_BAR;
;             PG8_LDA(At, 1, 1); PG8_STAGE(PG8_SA(1, 0), a3, voffA);
;             PG8_BAR; PG8_WAIT_L(0); PG8_MMA(1, 0, At, B0); PG8_BAR; PG8_SCHED;
;             PG8_STAGE(PG8_SB(1, 1), b3 + hstep, voffB);
;             PG8_WAIT_V(6); PG8_BAR; PG8_MMA(1, 1, At, B1); PG8_BAR;
;             }
;         }
;         if constexpr (ALIGN_EPI) { if (wr == 0) PG8_BAR; }
;         if constexpr (!Epi::AFTER_DRAIN) { E(acc, cur, wr, wc, fr, fq); S.done(cur); }
	s_add_i32 s46, s93, s63
	v_lshl_add_u64 v[146:147], v[146:147], 0, s[18:19]
	s_mov_b32 m0, s46
	ds_read_b128 v[196:199], v151 offset:49152
	ds_read_b128 v[200:203], v151 offset:50176
	ds_read_b128 v[204:207], v151 offset:51200
	ds_read_b128 v[208:211], v151 offset:52224
	ds_read_b128 v[212:215], v151 offset:53248
	ds_read_b128 v[216:219], v151 offset:54272
	ds_read_b128 v[220:223], v151 offset:55296
	ds_read_b128 v[224:227], v151 offset:56320
	global_load_lds_dwordx4 v[146:147], off
	v_lshl_add_u64 v[146:147], v[182:183], 0, s[18:19]
	s_add_i32 m0, s46, 0x2000
	s_add_i32 s46, s68, s63
	global_load_lds_dwordx4 v[146:147], off
	v_lshl_add_u64 v[146:147], v[184:185], 0, s[18:19]
	s_mov_b32 m0, s46
	s_nop 0
	global_load_lds_dwordx4 v[146:147], off
	v_lshl_add_u64 v[146:147], v[188:189], 0, s[18:19]
	s_add_i32 m0, s46, 0x2000
	s_nop 0
	global_load_lds_dwordx4 v[146:147], off
	v_lshl_add_u64 v[146:147], v[190:191], 0, s[18:19]
	s_mov_b32 m0, s0
	s_nop 0
	global_load_lds_dwordx4 v[146:147], off
	v_lshl_add_u64 v[146:147], v[228:229], 0, s[18:19]
	s_mov_b32 m0, s58
	s_nop 0
	global_load_lds_dwordx4 v[146:147], off
	s_waitcnt vmcnt(8)
	s_waitcnt lgkmcnt(0)
	s_barrier
	s_setprio 1
	s_waitcnt lgkmcnt(0)
	v_mfma_f32_16x16x32_bf16 v[60:63], v[138:141], v[196:199], v[60:63]
	v_mfma_f32_16x16x32_bf16 v[56:59], v[156:159], v[196:199], v[56:59]
	v_mfma_f32_16x16x32_bf16 v[44:47], v[138:141], v[204:207], v[44:47]
	v_mfma_f32_16x16x32_bf16 v[40:43], v[156:159], v[204:207], v[40:43]
	v_mfma_f32_16x16x32_bf16 v[28:31], v[138:141], v[212:215], v[28:31]
	v_mfma_f32_16x16x32_bf16 v[24:27], v[156:159], v[212:215], v[24:27]
	v_mfma_f32_16x16x32_bf16 v[12:15], v[138:141], v[220:223], v[12:15]
	v_mfma_f32_16x16x32_bf16 v[8:11], v[156:159], v[220:223], v[8:11]
	v_mfma_f32_16x16x32_bf16 v[60:63], v[142:145], v[200:203], v[60:63]
	v_mfma_f32_16x16x32_bf16 v[56:59], v[160:163], v[200:203], v[56:59]
	v_mfma_f32_16x16x32_bf16 v[44:47], v[142:145], v[208:211], v[44:47]
	v_mfma_f32_16x16x32_bf16 v[40:43], v[160:163], v[208:211], v[40:43]
	v_mfma_f32_16x16x32_bf16 v[28:31], v[142:145], v[216:219], v[28:31]
	v_mfma_f32_16x16x32_bf16 v[24:27], v[160:163], v[216:219], v[24:27]
	v_mfma_f32_16x16x32_bf16 v[12:15], v[142:145], v[224:227], v[12:15]
	v_mfma_f32_16x16x32_bf16 v[8:11], v[160:163], v[224:227], v[8:11]
	s_setprio 0
	s_setprio 1
	v_mfma_f32_16x16x32_bf16 v[52:55], v[164:167], v[196:199], v[52:55]
	v_mfma_f32_16x16x32_bf16 v[48:51], v[172:175], v[196:199], v[48:51]
	v_mfma_f32_16x16x32_bf16 v[36:39], v[164:167], v[204:207], v[36:39]
	v_mfma_f32_16x16x32_bf16 v[32:35], v[172:175], v[204:207], v[32:35]
	v_mfma_f32_16x16x32_bf16 v[20:23], v[164:167], v[212:215], v[20:23]
	v_mfma_f32_16x16x32_bf16 v[16:19], v[172:175], v[212:215], v[16:19]
	v_mfma_f32_16x16x32_bf16 v[4:7], v[164:167], v[220:223], v[4:7]
	v_mfma_f32_16x16x32_bf16 v[0:3], v[172:175], v[220:223], v[0:3]
	v_mfma_f32_16x16x32_bf16 v[52:55], v[168:171], v[200:203], v[52:55]
	v_mfma_f32_16x16x32_bf16 v[48:51], v[192:195], v[200:203], v[48:51]
	v_mfma_f32_16x16x32_bf16 v[36:39], v[168:171], v[208:211], v[36:39]
	v_mfma_f32_16x16x32_bf16 v[32:35], v[192:195], v[208:211], v[32:35]
	v_mfma_f32_16x16x32_bf16 v[20:23], v[168:171], v[216:219], v[20:23]
	v_mfma_f32_16x16x32_bf16 v[16:19], v[192:195], v[216:219], v[16:19]
	v_mfma_f32_16x16x32_bf16 v[4:7], v[168:171], v[224:227], v[4:7]
	v_mfma_f32_16x16x32_bf16 v[0:3], v[192:195], v[224:227], v[0:3]
	s_setprio 0
	s_barrier
	s_add_u32 s44, s44, 0x100
	s_addc_u32 s45, s45, 0
	s_add_u32 s86, s86, 0x100
	s_addc_u32 s87, s87, 0
	s_cmp_ge_u32 vcc_lo, s14
	s_mov_b32 s46, vcc_lo
	s_cbranch_scc0 .LBB0_218
	v_lshl_add_u32 v188, s26, 8, v148
	v_lshl_or_b32 v190, s17, 8, v150
	v_mov_b32_e32 v189, 0
	v_mov_b32_e32 v191, 0
	v_lshlrev_b64 v[182:183], 11, v[188:189]
	v_mov_b32_e32 v184, 0x10000
	v_lshl_add_u64 v[182:183], v[182:183], 0, v[190:191]
	v_mov_b32_e32 v185, 0
	v_lshl_add_u64 v[182:183], v[182:183], 1, s[12:13]
	global_load_dwordx4 v[164:167], v[182:183], off
	global_load_dwordx4 v[168:171], v[182:183], off offset:256
	v_lshl_add_u64 v[182:183], v[182:183], 0, v[184:185]
	global_load_dwordx4 v[172:175], v[182:183], off
	global_load_dwordx4 v[192:195], v[182:183], off offset:256
	v_lshl_add_u64 v[182:183], v[182:183], 0, v[184:185]
	global_load_dwordx4 v[196:199], v[182:183], off
	global_load_dwordx4 v[200:203], v[182:183], off offset:256
	v_lshl_add_u64 v[182:183], v[182:183], 0, v[184:185]
	global_load_dwordx4 v[204:207], v[182:183], off
	global_load_dwordx4 v[208:211], v[182:183], off offset:256
	v_mov_b32_e32 v184, 0x50000
	s_nop 0
	v_lshl_add_u64 v[182:183], v[182:183], 0, v[184:185]
	v_mov_b32_e32 v184, 0x10000
	global_load_dwordx4 v[212:215], v[182:183], off
	global_load_dwordx4 v[216:219], v[182:183], off offset:256
	v_lshl_add_u64 v[182:183], v[182:183], 0, v[184:185]
	global_load_dwordx4 v[220:223], v[182:183], off
	global_load_dwordx4 v[224:227], v[182:183], off offset:256
	v_lshl_add_u64 v[182:183], v[182:183], 0, v[184:185]
	global_load_dwordx4 v[228:231], v[182:183], off
	global_load_dwordx4 v[232:235], v[182:183], off offset:256
	v_lshl_add_u64 v[182:183], v[182:183], 0, v[184:185]
	global_load_dwordx4 v[240:243], v[182:183], off
	global_load_dwordx4 v[244:247], v[182:183], off offset:256
	s_and_b64 vcc, exec, s[36:37]
	s_cbranch_vccz .LBB0_221
	s_barrier
.LBB0_221:
	s_waitcnt vmcnt(0)
	v_lshl_add_u32 v140, s26, 8, v148
	v_lshl_or_b32 v138, s17, 8, v150
	v_ashrrev_i32_e32 v141, 31, v140
	v_ashrrev_i32_e32 v139, 31, v138
	v_lshlrev_b64 v[142:143], 11, v[140:141]
	v_lshl_add_u64 v[144:145], v[142:143], 0, v[138:139]
	v_lshl_add_u64 v[146:147], v[144:145], 1, s[12:13]
	v_cndmask_b32_e64 v142, 0, 1, s[78:79]
	v_cmp_ne_u32_e64 s[44:45], 1, v142
	s_andn2_b64 vcc, exec, s[78:79]
	v_lshlrev_b32_e32 v142, 16, v164
	v_and_b32_e32 v143, 0xffff0000, v164
	v_lshlrev_b32_e32 v156, 16, v165
	v_and_b32_e32 v157, 0xffff0000, v165
	v_lshlrev_b32_e32 v160, 16, v166
	v_and_b32_e32 v161, 0xffff0000, v166
	v_lshlrev_b32_e32 v158, 16, v167
	v_and_b32_e32 v159, 0xffff0000, v167
	v_pk_fma_f32 v[126:127], s[10:11], v[126:127], v[156:157]
	v_pk_fma_f32 v[124:125], s[76:77], v[124:125], v[142:143]
	v_pk_fma_f32 v[122:123], s[10:11], v[122:123], v[158:159]
	v_pk_fma_f32 v[120:121], s[76:77], v[120:121], v[160:161]
	v_lshl_add_u64 v[142:143], v[144:145], 2, s[28:29]
	s_cbranch_vccnz .LBB0_304
	global_store_dwordx4 v[142:143], v[124:127], off
	global_store_dwordx4 v[142:143], v[120:123], off offset:16
	s_mov_b32 s96, s91
	s_cbranch_execnz .LBB0_224

; __device__ __forceinline__ unsigned cvt_pk_bf16(float lo, float hi) { unsigned r; asm volatile("v_cvt_pk_bf16_f32 %0, %1, %2" : "=v"(r) : "v"(lo), "v"(hi)); return r; }
;     __device__ __forceinline__ void operator()(const f32x4 (&acc)[2][2][4][2], const Unit& u, int wr, int wc, int fr, int fq) const {
;     ...
;                 for (int bj = 0; bj < 2; ++bj) { const size_t off = (size_t)row * 2048 + col0 + bj * HALF;
;                     f32x4 b0, b1;
;                     if (base32) { b0 = *(const f32x4*)(base32 + off); b1 = *(const f32x4*)(base32 + off + 4); }
;                     else { const u32x4 bw = *(const u32x4*)(xb + off);
;                         b0 = (f32x4){__uint_as_float(bw.x << 16), __uint_as_float(bw.x & 0xffff0000u), __uint_as_float(bw.y << 16), __uint_as_float(bw.y & 0xffff0000u)};
;                         b1 = (f32x4){__uint_as_float(bw.z << 16), __uint_as_float(bw.z & 0xffff0000u), __uint_as_float(bw.w << 16), __uint_as_float(bw.w & 0xffff0000u)}; }
;                     const f32x4 x0 = b0 + acc[ai][bj][m][0] * alpha, x1 = b1 + acc[ai][bj][m][1] * alpha;
;                     q += (x0[0] * x0[0] + x0[1] * x0[1]) + (x0[2] * x0[2] + x0[3] * x0[3]) + (x1[0] * x1[0] + x1[1] * x1[1]) + (x1[2] * x1[2] + x1[3] * x1[3]);
;                     if (out32) { *(f32x4*)(out32 + off) = x0; *(f32x4*)(out32 + off + 4) = x1; }
;                     else { u32x4 w; w.x = cvt_pk_bf16(x0[0], x0[1]); w.y = cvt_pk_bf16(x0[2], x0[3]); w.z = cvt_pk_bf16(x1[0], x1[1]); w.w = cvt_pk_bf16(x1[2], x1[3]);
;                         *(u32x4*)(xb + off) = w; } }
.LBB0_224:
	v_lshlrev_b64 v[144:145], 1, v[144:145]
	v_or_b32_e32 v144, 0x100, v144
	v_lshl_add_u64 v[144:145], s[12:13], 0, v[144:145]
	s_and_b64 vcc, exec, s[44:45]
	s_mov_b32 s91, s35
	v_lshlrev_b32_e32 v146, 16, v168
	v_and_b32_e32 v147, 0xffff0000, v168
	v_lshlrev_b32_e32 v156, 16, v169
	v_and_b32_e32 v157, 0xffff0000, v169
	v_lshlrev_b32_e32 v160, 16, v170
	v_and_b32_e32 v161, 0xffff0000, v170
	v_lshlrev_b32_e32 v158, 16, v171
	v_and_b32_e32 v159, 0xffff0000, v171
	v_pk_fma_f32 v[118:119], s[10:11], v[118:119], v[156:157]
	v_pk_fma_f32 v[116:117], s[76:77], v[116:117], v[146:147]
	v_pk_fma_f32 v[114:115], s[10:11], v[114:115], v[158:159]
	v_pk_fma_f32 v[112:113], s[76:77], v[112:113], v[160:161]
	s_cbranch_vccnz .LBB0_305
	global_store_dwordx4 v[142:143], v[116:119], off offset:512
	global_store_dwordx4 v[142:143], v[112:115], off offset:528
	s_mov_b32 s35, s90
	s_mov_b32 s90, s30
	s_cbranch_execnz .LBB0_227

; __device__ __forceinline__ unsigned cvt_pk_bf16(float lo, float hi) { unsigned r; asm volatile("v_cvt_pk_bf16_f32 %0, %1, %2" : "=v"(r) : "v"(lo), "v"(hi)); return r; }
;     __device__ __forceinline__ void operator()(const f32x4 (&acc)[2][2][4][2], const Unit& u, int wr, int wc, int fr, int fq) const {
;     ...
;                 for (int bj = 0; bj < 2; ++bj) { const size_t off = (size_t)row * 2048 + col0 + bj * HALF;
;                     f32x4 b0, b1;
;                     if (base32) { b0 = *(const f32x4*)(base32 + off); b1 = *(const f32x4*)(base32 + off + 4); }
;                     else { const u32x4 bw = *(const u32x4*)(xb + off);
;                         b0 = (f32x4){__uint_as_float(bw.x << 16), __uint_as_float(bw.x & 0xffff0000u), __uint_as_float(bw.y << 16), __uint_as_float(bw.y & 0xffff0000u)};
;                         b1 = (f32x4){__uint_as_float(bw.z << 16), __uint_as_float(bw.z & 0xffff0000u), __uint_as_float(bw.w << 16), __uint_as_float(bw.w & 0xffff0000u)}; }
;                     const f32x4 x0 = b0 + acc[ai][bj][m][0] * alpha, x1 = b1 + acc[ai][bj][m][1] * alpha;
;                     q += (x0[0] * x0[0] + x0[1] * x0[1]) + (x0[2] * x0[2] + x0[3] * x0[3]) + (x1[0] * x1[0] + x1[1] * x1[1]) + (x1[2] * x1[2] + x1[3] * x1[3]);
;                     if (out32) { *(f32x4*)(out32 + off) = x0; *(f32x4*)(out32 + off + 4) = x1; }
;                     else { u32x4 w; w.x = cvt_pk_bf16(x0[0], x0[1]); w.y = cvt_pk_bf16(x0[2], x0[3]); w.z = cvt_pk_bf16(x1[0], x1[1]); w.w = cvt_pk_bf16(x1[2], x1[3]);
;                         *(u32x4*)(xb + off) = w; } }
.LBB0_231:
	v_or_b32_e32 v112, 16, v140
	s_waitcnt lgkmcnt(0)
	v_ashrrev_i32_e32 v113, 31, v112
	v_lshlrev_b64 v[114:115], 11, v[112:113]
	v_lshl_add_u64 v[116:117], v[114:115], 0, v[138:139]
	v_lshl_add_u64 v[118:119], v[116:117], 1, s[12:13]
	s_and_b64 vcc, exec, s[44:45]
	v_lshlrev_b32_e32 v114, 16, v172
	v_and_b32_e32 v115, 0xffff0000, v172
	v_lshlrev_b32_e32 v120, 16, v173
	v_and_b32_e32 v121, 0xffff0000, v173
	v_lshlrev_b32_e32 v124, 16, v174
	v_and_b32_e32 v125, 0xffff0000, v174
	v_lshlrev_b32_e32 v122, 16, v175
	v_and_b32_e32 v123, 0xffff0000, v175
	v_pk_fma_f32 v[110:111], s[10:11], v[110:111], v[120:121]
	v_pk_fma_f32 v[108:109], s[76:77], v[108:109], v[114:115]
	v_pk_fma_f32 v[106:107], s[10:11], v[106:107], v[122:123]
	v_pk_fma_f32 v[104:105], s[76:77], v[104:105], v[124:125]
	v_lshl_add_u64 v[114:115], v[116:117], 2, s[28:29]
	s_cbranch_vccnz .LBB0_306
	global_store_dwordx4 v[114:115], v[108:111], off
	global_store_dwordx4 v[114:115], v[104:107], off offset:16
	s_cbranch_execnz .LBB0_234

; __device__ __forceinline__ unsigned cvt_pk_bf16(float lo, float hi) { unsigned r; asm volatile("v_cvt_pk_bf16_f32 %0, %1, %2" : "=v"(r) : "v"(lo), "v"(hi)); return r; }
;     __device__ __forceinline__ void operator()(const f32x4 (&acc)[2][2][4][2], const Unit& u, int wr, int wc, int fr, int fq) const {
;     ...
;                 for (int bj = 0; bj < 2; ++bj) { const size_t off = (size_t)row * 2048 + col0 + bj * HALF;
;                     f32x4 b0, b1;
;                     if (base32) { b0 = *(const f32x4*)(base32 + off); b1 = *(const f32x4*)(base32 + off + 4); }
;                     else { const u32x4 bw = *(const u32x4*)(xb + off);
;                         b0 = (f32x4){__uint_as_float(bw.x << 16), __uint_as_float(bw.x & 0xffff0000u), __uint_as_float(bw.y << 16), __uint_as_float(bw.y & 0xffff0000u)};
;                         b1 = (f32x4){__uint_as_float(bw.z << 16), __uint_as_float(bw.z & 0xffff0000u), __uint_as_float(bw.w << 16), __uint_as_float(bw.w & 0xffff0000u)}; }
;                     const f32x4 x0 = b0 + acc[ai][bj][m][0] * alpha, x1 = b1 + acc[ai][bj][m][1] * alpha;
;                     q += (x0[0] * x0[0] + x0[1] * x0[1]) + (x0[2] * x0[2] + x0[3] * x0[3]) + (x1[0] * x1[0] + x1[1] * x1[1]) + (x1[2] * x1[2] + x1[3] * x1[3]);
;                     if (out32) { *(f32x4*)(out32 + off) = x0; *(f32x4*)(out32 + off + 4) = x1; }
;                     else { u32x4 w; w.x = cvt_pk_bf16(x0[0], x0[1]); w.y = cvt_pk_bf16(x0[2], x0[3]); w.z = cvt_pk_bf16(x1[0], x1[1]); w.w = cvt_pk_bf16(x1[2], x1[3]);
;                         *(u32x4*)(xb + off) = w; } }
.LBB0_234:
	v_lshlrev_b64 v[116:117], 1, v[116:117]
	v_or_b32_e32 v116, 0x100, v116
	v_lshl_add_u64 v[116:117], s[12:13], 0, v[116:117]
	s_and_b64 vcc, exec, s[44:45]
	v_lshlrev_b32_e32 v122, 16, v192
	v_and_b32_e32 v123, 0xffff0000, v192
	v_lshlrev_b32_e32 v118, 16, v193
	v_and_b32_e32 v119, 0xffff0000, v193
	v_lshlrev_b32_e32 v124, 16, v194
	v_and_b32_e32 v125, 0xffff0000, v194
	v_lshlrev_b32_e32 v120, 16, v195
	v_and_b32_e32 v121, 0xffff0000, v195
	v_pk_fma_f32 v[102:103], s[10:11], v[102:103], v[118:119]
	v_pk_fma_f32 v[100:101], s[76:77], v[100:101], v[122:123]
	v_pk_fma_f32 v[98:99], s[10:11], v[98:99], v[120:121]
	v_pk_fma_f32 v[96:97], s[76:77], v[96:97], v[124:125]
	s_cbranch_vccnz .LBB0_307
	global_store_dwordx4 v[114:115], v[100:103], off offset:512
	global_store_dwordx4 v[114:115], v[96:99], off offset:528
	s_cbranch_execnz .LBB0_237

; __device__ __forceinline__ unsigned cvt_pk_bf16(float lo, float hi) { unsigned r; asm volatile("v_cvt_pk_bf16_f32 %0, %1, %2" : "=v"(r) : "v"(lo), "v"(hi)); return r; }
;     __device__ __forceinline__ void operator()(const f32x4 (&acc)[2][2][4][2], const Unit& u, int wr, int wc, int fr, int fq) const {
;     ...
;                 for (int bj = 0; bj < 2; ++bj) { const size_t off = (size_t)row * 2048 + col0 + bj * HALF;
;                     f32x4 b0, b1;
;                     if (base32) { b0 = *(const f32x4*)(base32 + off); b1 = *(const f32x4*)(base32 + off + 4); }
;                     else { const u32x4 bw = *(const u32x4*)(xb + off);
;                         b0 = (f32x4){__uint_as_float(bw.x << 16), __uint_as_float(bw.x & 0xffff0000u), __uint_as_float(bw.y << 16), __uint_as_float(bw.y & 0xffff0000u)};
;                         b1 = (f32x4){__uint_as_float(bw.z << 16), __uint_as_float(bw.z & 0xffff0000u), __uint_as_float(bw.w << 16), __uint_as_float(bw.w & 0xffff0000u)}; }
;                     const f32x4 x0 = b0 + acc[ai][bj][m][0] * alpha, x1 = b1 + acc[ai][bj][m][1] * alpha;
;                     q += (x0[0] * x0[0] + x0[1] * x0[1]) + (x0[2] * x0[2] + x0[3] * x0[3]) + (x1[0] * x1[0] + x1[1] * x1[1]) + (x1[2] * x1[2] + x1[3] * x1[3]);
;                     if (out32) { *(f32x4*)(out32 + off) = x0; *(f32x4*)(out32 + off + 4) = x1; }
;                     else { u32x4 w; w.x = cvt_pk_bf16(x0[0], x0[1]); w.y = cvt_pk_bf16(x0[2], x0[3]); w.z = cvt_pk_bf16(x1[0], x1[1]); w.w = cvt_pk_bf16(x1[2], x1[3]);
;                         *(u32x4*)(xb + off) = w; } }
.LBB0_241:
	v_or_b32_e32 v96, 32, v140
	s_waitcnt lgkmcnt(0)
	v_ashrrev_i32_e32 v97, 31, v96
	v_lshlrev_b64 v[98:99], 11, v[96:97]
	v_lshl_add_u64 v[100:101], v[98:99], 0, v[138:139]
	v_lshl_add_u64 v[102:103], v[100:101], 1, s[12:13]
	s_and_b64 vcc, exec, s[44:45]
	v_lshlrev_b32_e32 v98, 16, v196
	v_and_b32_e32 v99, 0xffff0000, v196
	v_lshlrev_b32_e32 v104, 16, v197
	v_and_b32_e32 v105, 0xffff0000, v197
	v_lshlrev_b32_e32 v108, 16, v198
	v_and_b32_e32 v109, 0xffff0000, v198
	v_lshlrev_b32_e32 v106, 16, v199
	v_and_b32_e32 v107, 0xffff0000, v199
	v_pk_fma_f32 v[94:95], s[10:11], v[94:95], v[104:105]
	v_pk_fma_f32 v[92:93], s[76:77], v[92:93], v[98:99]
	v_pk_fma_f32 v[90:91], s[10:11], v[90:91], v[106:107]
	v_pk_fma_f32 v[88:89], s[76:77], v[88:89], v[108:109]
	v_lshl_add_u64 v[98:99], v[100:101], 2, s[28:29]
	s_cbranch_vccnz .LBB0_308
	global_store_dwordx4 v[98:99], v[92:95], off
	global_store_dwordx4 v[98:99], v[88:91], off offset:16
	s_cbranch_execnz .LBB0_244

; __device__ __forceinline__ unsigned cvt_pk_bf16(float lo, float hi) { unsigned r; asm volatile("v_cvt_pk_bf16_f32 %0, %1, %2" : "=v"(r) : "v"(lo), "v"(hi)); return r; }
;     __device__ __forceinline__ void operator()(const f32x4 (&acc)[2][2][4][2], const Unit& u, int wr, int wc, int fr, int fq) const {
;     ...
;                 for (int bj = 0; bj < 2; ++bj) { const size_t off = (size_t)row * 2048 + col0 + bj * HALF;
;                     f32x4 b0, b1;
;                     if (base32) { b0 = *(const f32x4*)(base32 + off); b1 = *(const f32x4*)(base32 + off + 4); }
;                     else { const u32x4 bw = *(const u32x4*)(xb + off);
;                         b0 = (f32x4){__uint_as_float(bw.x << 16), __uint_as_float(bw.x & 0xffff0000u), __uint_as_float(bw.y << 16), __uint_as_float(bw.y & 0xffff0000u)};
;                         b1 = (f32x4){__uint_as_float(bw.z << 16), __uint_as_float(bw.z & 0xffff0000u), __uint_as_float(bw.w << 16), __uint_as_float(bw.w & 0xffff0000u)}; }
;                     const f32x4 x0 = b0 + acc[ai][bj][m][0] * alpha, x1 = b1 + acc[ai][bj][m][1] * alpha;
;                     q += (x0[0] * x0[0] + x0[1] * x0[1]) + (x0[2] * x0[2] + x0[3] * x0[3]) + (x1[0] * x1[0] + x1[1] * x1[1]) + (x1[2] * x1[2] + x1[3] * x1[3]);
;                     if (out32) { *(f32x4*)(out32 + off) = x0; *(f32x4*)(out32 + off + 4) = x1; }
;                     else { u32x4 w; w.x = cvt_pk_bf16(x0[0], x0[1]); w.y = cvt_pk_bf16(x0[2], x0[3]); w.z = cvt_pk_bf16(x1[0], x1[1]); w.w = cvt_pk_bf16(x1[2], x1[3]);
;                         *(u32x4*)(xb + off) = w; } }
.LBB0_244:
	v_lshlrev_b64 v[100:101], 1, v[100:101]
	v_or_b32_e32 v100, 0x100, v100
	v_lshl_add_u64 v[100:101], s[12:13], 0, v[100:101]
	s_and_b64 vcc, exec, s[44:45]
	v_lshlrev_b32_e32 v106, 16, v200
	v_and_b32_e32 v107, 0xffff0000, v200
	v_lshlrev_b32_e32 v102, 16, v201
	v_and_b32_e32 v103, 0xffff0000, v201
	v_lshlrev_b32_e32 v108, 16, v202
	v_and_b32_e32 v109, 0xffff0000, v202
	v_lshlrev_b32_e32 v104, 16, v203
	v_and_b32_e32 v105, 0xffff0000, v203
	v_pk_fma_f32 v[86:87], s[10:11], v[86:87], v[102:103]
	v_pk_fma_f32 v[84:85], s[76:77], v[84:85], v[106:107]
	v_pk_fma_f32 v[82:83], s[10:11], v[82:83], v[104:105]
	v_pk_fma_f32 v[80:81], s[76:77], v[80:81], v[108:109]
	s_cbranch_vccnz .LBB0_309
	global_store_dwordx4 v[98:99], v[84:87], off offset:512
	global_store_dwordx4 v[98:99], v[80:83], off offset:528
	s_cbranch_execnz .LBB0_247

; __device__ __forceinline__ unsigned cvt_pk_bf16(float lo, float hi) { unsigned r; asm volatile("v_cvt_pk_bf16_f32 %0, %1, %2" : "=v"(r) : "v"(lo), "v"(hi)); return r; }
;     __device__ __forceinline__ void operator()(const f32x4 (&acc)[2][2][4][2], const Unit& u, int wr, int wc, int fr, int fq) const {
;     ...
;                 for (int bj = 0; bj < 2; ++bj) { const size_t off = (size_t)row * 2048 + col0 + bj * HALF;
;                     f32x4 b0, b1;
;                     if (base32) { b0 = *(const f32x4*)(base32 + off); b1 = *(const f32x4*)(base32 + off + 4); }
;                     else { const u32x4 bw = *(const u32x4*)(xb + off);
;                         b0 = (f32x4){__uint_as_float(bw.x << 16), __uint_as_float(bw.x & 0xffff0000u), __uint_as_float(bw.y << 16), __uint_as_float(bw.y & 0xffff0000u)};
;                         b1 = (f32x4){__uint_as_float(bw.z << 16), __uint_as_float(bw.z & 0xffff0000u), __uint_as_float(bw.w << 16), __uint_as_float(bw.w & 0xffff0000u)}; }
;                     const f32x4 x0 = b0 + acc[ai][bj][m][0] * alpha, x1 = b1 + acc[ai][bj][m][1] * alpha;
;                     q += (x0[0] * x0[0] + x0[1] * x0[1]) + (x0[2] * x0[2] + x0[3] * x0[3]) + (x1[0] * x1[0] + x1[1] * x1[1]) + (x1[2] * x1[2] + x1[3] * x1[3]);
;                     if (out32) { *(f32x4*)(out32 + off) = x0; *(f32x4*)(out32 + off + 4) = x1; }
;                     else { u32x4 w; w.x = cvt_pk_bf16(x0[0], x0[1]); w.y = cvt_pk_bf16(x0[2], x0[3]); w.z = cvt_pk_bf16(x1[0], x1[1]); w.w = cvt_pk_bf16(x1[2], x1[3]);
;                         *(u32x4*)(xb + off) = w; } }
.LBB0_251:
	v_or_b32_e32 v80, 48, v140
	s_waitcnt lgkmcnt(0)
	v_ashrrev_i32_e32 v81, 31, v80
	v_lshlrev_b64 v[82:83], 11, v[80:81]
	v_lshl_add_u64 v[84:85], v[82:83], 0, v[138:139]
	v_lshl_add_u64 v[86:87], v[84:85], 1, s[12:13]
	s_and_b64 vcc, exec, s[44:45]
	v_lshlrev_b32_e32 v82, 16, v204
	v_and_b32_e32 v83, 0xffff0000, v204
	v_lshlrev_b32_e32 v88, 16, v205
	v_and_b32_e32 v89, 0xffff0000, v205
	v_lshlrev_b32_e32 v92, 16, v206
	v_and_b32_e32 v93, 0xffff0000, v206
	v_lshlrev_b32_e32 v90, 16, v207
	v_and_b32_e32 v91, 0xffff0000, v207
	v_pk_fma_f32 v[78:79], s[10:11], v[78:79], v[88:89]
	v_pk_fma_f32 v[76:77], s[76:77], v[76:77], v[82:83]
	v_pk_fma_f32 v[74:75], s[10:11], v[74:75], v[90:91]
	v_pk_fma_f32 v[72:73], s[76:77], v[72:73], v[92:93]
	v_lshl_add_u64 v[82:83], v[84:85], 2, s[28:29]
	s_cbranch_vccnz .LBB0_310
	global_store_dwordx4 v[82:83], v[76:79], off
	global_store_dwordx4 v[82:83], v[72:75], off offset:16
	s_cbranch_execnz .LBB0_254

; __device__ __forceinline__ unsigned cvt_pk_bf16(float lo, float hi) { unsigned r; asm volatile("v_cvt_pk_bf16_f32 %0, %1, %2" : "=v"(r) : "v"(lo), "v"(hi)); return r; }
;     __device__ __forceinline__ void operator()(const f32x4 (&acc)[2][2][4][2], const Unit& u, int wr, int wc, int fr, int fq) const {
;     ...
;                 for (int bj = 0; bj < 2; ++bj) { const size_t off = (size_t)row * 2048 + col0 + bj * HALF;
;                     f32x4 b0, b1;
;                     if (base32) { b0 = *(const f32x4*)(base32 + off); b1 = *(const f32x4*)(base32 + off + 4); }
;                     else { const u32x4 bw = *(const u32x4*)(xb + off);
;                         b0 = (f32x4){__uint_as_float(bw.x << 16), __uint_as_float(bw.x & 0xffff0000u), __uint_as_float(bw.y << 16), __uint_as_float(bw.y & 0xffff0000u)};
;                         b1 = (f32x4){__uint_as_float(bw.z << 16), __uint_as_float(bw.z & 0xffff0000u), __uint_as_float(bw.w << 16), __uint_as_float(bw.w & 0xffff0000u)}; }
;                     const f32x4 x0 = b0 + acc[ai][bj][m][0] * alpha, x1 = b1 + acc[ai][bj][m][1] * alpha;
;                     q += (x0[0] * x0[0] + x0[1] * x0[1]) + (x0[2] * x0[2] + x0[3] * x0[3]) + (x1[0] * x1[0] + x1[1] * x1[1]) + (x1[2] * x1[2] + x1[3] * x1[3]);
;                     if (out32) { *(f32x4*)(out32 + off) = x0; *(f32x4*)(out32 + off + 4) = x1; }
;                     else { u32x4 w; w.x = cvt_pk_bf16(x0[0], x0[1]); w.y = cvt_pk_bf16(x0[2], x0[3]); w.z = cvt_pk_bf16(x1[0], x1[1]); w.w = cvt_pk_bf16(x1[2], x1[3]);
;                         *(u32x4*)(xb + off) = w; } }
.LBB0_254:
	v_lshlrev_b64 v[84:85], 1, v[84:85]
	v_or_b32_e32 v84, 0x100, v84
	v_lshl_add_u64 v[84:85], s[12:13], 0, v[84:85]
	s_and_b64 vcc, exec, s[44:45]
	v_lshlrev_b32_e32 v90, 16, v208
	v_and_b32_e32 v91, 0xffff0000, v208
	v_lshlrev_b32_e32 v86, 16, v209
	v_and_b32_e32 v87, 0xffff0000, v209
	v_lshlrev_b32_e32 v92, 16, v210
	v_and_b32_e32 v93, 0xffff0000, v210
	v_lshlrev_b32_e32 v88, 16, v211
	v_and_b32_e32 v89, 0xffff0000, v211
	v_pk_fma_f32 v[70:71], s[10:11], v[70:71], v[86:87]
	v_pk_fma_f32 v[68:69], s[76:77], v[68:69], v[90:91]
	v_pk_fma_f32 v[66:67], s[10:11], v[66:67], v[88:89]
	v_pk_fma_f32 v[64:65], s[76:77], v[64:65], v[92:93]
	s_cbranch_vccnz .LBB0_311
	global_store_dwordx4 v[82:83], v[68:71], off offset:512
	global_store_dwordx4 v[82:83], v[64:67], off offset:528
	s_cbranch_execnz .LBB0_257

; __device__ __forceinline__ unsigned cvt_pk_bf16(float lo, float hi) { unsigned r; asm volatile("v_cvt_pk_bf16_f32 %0, %1, %2" : "=v"(r) : "v"(lo), "v"(hi)); return r; }
;     __device__ __forceinline__ void operator()(const f32x4 (&acc)[2][2][4][2], const Unit& u, int wr, int wc, int fr, int fq) const {
;     ...
;                 for (int bj = 0; bj < 2; ++bj) { const size_t off = (size_t)row * 2048 + col0 + bj * HALF;
;                     f32x4 b0, b1;
;                     if (base32) { b0 = *(const f32x4*)(base32 + off); b1 = *(const f32x4*)(base32 + off + 4); }
;                     else { const u32x4 bw = *(const u32x4*)(xb + off);
;                         b0 = (f32x4){__uint_as_float(bw.x << 16), __uint_as_float(bw.x & 0xffff0000u), __uint_as_float(bw.y << 16), __uint_as_float(bw.y & 0xffff0000u)};
;                         b1 = (f32x4){__uint_as_float(bw.z << 16), __uint_as_float(bw.z & 0xffff0000u), __uint_as_float(bw.w << 16), __uint_as_float(bw.w & 0xffff0000u)}; }
;                     const f32x4 x0 = b0 + acc[ai][bj][m][0] * alpha, x1 = b1 + acc[ai][bj][m][1] * alpha;
;                     q += (x0[0] * x0[0] + x0[1] * x0[1]) + (x0[2] * x0[2] + x0[3] * x0[3]) + (x1[0] * x1[0] + x1[1] * x1[1]) + (x1[2] * x1[2] + x1[3] * x1[3]);
;                     if (out32) { *(f32x4*)(out32 + off) = x0; *(f32x4*)(out32 + off + 4) = x1; }
;                     else { u32x4 w; w.x = cvt_pk_bf16(x0[0], x0[1]); w.y = cvt_pk_bf16(x0[2], x0[3]); w.z = cvt_pk_bf16(x1[0], x1[1]); w.w = cvt_pk_bf16(x1[2], x1[3]);
;                         *(u32x4*)(xb + off) = w; } }
.LBB0_261:
	v_add_u32_e32 v64, 0x80, v140
	s_waitcnt lgkmcnt(0)
	v_ashrrev_i32_e32 v65, 31, v64
	v_lshlrev_b64 v[66:67], 11, v[64:65]
	v_lshl_add_u64 v[68:69], v[66:67], 0, v[138:139]
	v_lshl_add_u64 v[70:71], v[68:69], 1, s[12:13]
	s_and_b64 vcc, exec, s[44:45]
	v_lshlrev_b32_e32 v66, 16, v212
	v_and_b32_e32 v67, 0xffff0000, v212
	v_lshlrev_b32_e32 v72, 16, v213
	v_and_b32_e32 v73, 0xffff0000, v213
	v_lshlrev_b32_e32 v76, 16, v214
	v_and_b32_e32 v77, 0xffff0000, v214
	v_lshlrev_b32_e32 v74, 16, v215
	v_and_b32_e32 v75, 0xffff0000, v215
	v_pk_fma_f32 v[62:63], s[10:11], v[62:63], v[72:73]
	v_pk_fma_f32 v[60:61], s[76:77], v[60:61], v[66:67]
	v_pk_fma_f32 v[58:59], s[10:11], v[58:59], v[74:75]
	v_pk_fma_f32 v[56:57], s[76:77], v[56:57], v[76:77]
	v_lshl_add_u64 v[66:67], v[68:69], 2, s[28:29]
	s_cbranch_vccnz .LBB0_312
	global_store_dwordx4 v[66:67], v[60:63], off
	global_store_dwordx4 v[66:67], v[56:59], off offset:16
	s_cbranch_execnz .LBB0_264

; __device__ __forceinline__ unsigned cvt_pk_bf16(float lo, float hi) { unsigned r; asm volatile("v_cvt_pk_bf16_f32 %0, %1, %2" : "=v"(r) : "v"(lo), "v"(hi)); return r; }
;     __device__ __forceinline__ void operator()(const f32x4 (&acc)[2][2][4][2], const Unit& u, int wr, int wc, int fr, int fq) const {
;     ...
;                 for (int bj = 0; bj < 2; ++bj) { const size_t off = (size_t)row * 2048 + col0 + bj * HALF;
;                     f32x4 b0, b1;
;                     if (base32) { b0 = *(const f32x4*)(base32 + off); b1 = *(const f32x4*)(base32 + off + 4); }
;                     else { const u32x4 bw = *(const u32x4*)(xb + off);
;                         b0 = (f32x4){__uint_as_float(bw.x << 16), __uint_as_float(bw.x & 0xffff0000u), __uint_as_float(bw.y << 16), __uint_as_float(bw.y & 0xffff0000u)};
;                         b1 = (f32x4){__uint_as_float(bw.z << 16), __uint_as_float(bw.z & 0xffff0000u), __uint_as_float(bw.w << 16), __uint_as_float(bw.w & 0xffff0000u)}; }
;                     const f32x4 x0 = b0 + acc[ai][bj][m][0] * alpha, x1 = b1 + acc[ai][bj][m][1] * alpha;
;                     q += (x0[0] * x0[0] + x0[1] * x0[1]) + (x0[2] * x0[2] + x0[3] * x0[3]) + (x1[0] * x1[0] + x1[1] * x1[1]) + (x1[2] * x1[2] + x1[3] * x1[3]);
;                     if (out32) { *(f32x4*)(out32 + off) = x0; *(f32x4*)(out32 + off + 4) = x1; }
;                     else { u32x4 w; w.x = cvt_pk_bf16(x0[0], x0[1]); w.y = cvt_pk_bf16(x0[2], x0[3]); w.z = cvt_pk_bf16(x1[0], x1[1]); w.w = cvt_pk_bf16(x1[2], x1[3]);
;                         *(u32x4*)(xb + off) = w; } }
.LBB0_264:
	v_lshlrev_b64 v[68:69], 1, v[68:69]
	v_or_b32_e32 v68, 0x100, v68
	v_lshl_add_u64 v[68:69], s[12:13], 0, v[68:69]
	s_and_b64 vcc, exec, s[44:45]
	v_lshlrev_b32_e32 v74, 16, v216
	v_and_b32_e32 v75, 0xffff0000, v216
	v_lshlrev_b32_e32 v70, 16, v217
	v_and_b32_e32 v71, 0xffff0000, v217
	v_lshlrev_b32_e32 v76, 16, v218
	v_and_b32_e32 v77, 0xffff0000, v218
	v_lshlrev_b32_e32 v72, 16, v219
	v_and_b32_e32 v73, 0xffff0000, v219
	v_pk_fma_f32 v[54:55], s[10:11], v[54:55], v[70:71]
	v_pk_fma_f32 v[52:53], s[76:77], v[52:53], v[74:75]
	v_pk_fma_f32 v[50:51], s[10:11], v[50:51], v[72:73]
	v_pk_fma_f32 v[48:49], s[76:77], v[48:49], v[76:77]
	s_cbranch_vccnz .LBB0_313
	global_store_dwordx4 v[66:67], v[52:55], off offset:512
	global_store_dwordx4 v[66:67], v[48:51], off offset:528
	s_cbranch_execnz .LBB0_267

; __device__ __forceinline__ unsigned cvt_pk_bf16(float lo, float hi) { unsigned r; asm volatile("v_cvt_pk_bf16_f32 %0, %1, %2" : "=v"(r) : "v"(lo), "v"(hi)); return r; }
;     __device__ __forceinline__ void operator()(const f32x4 (&acc)[2][2][4][2], const Unit& u, int wr, int wc, int fr, int fq) const {
;     ...
;                 for (int bj = 0; bj < 2; ++bj) { const size_t off = (size_t)row * 2048 + col0 + bj * HALF;
;                     f32x4 b0, b1;
;                     if (base32) { b0 = *(const f32x4*)(base32 + off); b1 = *(const f32x4*)(base32 + off + 4); }
;                     else { const u32x4 bw = *(const u32x4*)(xb + off);
;                         b0 = (f32x4){__uint_as_float(bw.x << 16), __uint_as_float(bw.x & 0xffff0000u), __uint_as_float(bw.y << 16), __uint_as_float(bw.y & 0xffff0000u)};
;                         b1 = (f32x4){__uint_as_float(bw.z << 16), __uint_as_float(bw.z & 0xffff0000u), __uint_as_float(bw.w << 16), __uint_as_float(bw.w & 0xffff0000u)}; }
;                     const f32x4 x0 = b0 + acc[ai][bj][m][0] * alpha, x1 = b1 + acc[ai][bj][m][1] * alpha;
;                     q += (x0[0] * x0[0] + x0[1] * x0[1]) + (x0[2] * x0[2] + x0[3] * x0[3]) + (x1[0] * x1[0] + x1[1] * x1[1]) + (x1[2] * x1[2] + x1[3] * x1[3]);
;                     if (out32) { *(f32x4*)(out32 + off) = x0; *(f32x4*)(out32 + off + 4) = x1; }
;                     else { u32x4 w; w.x = cvt_pk_bf16(x0[0], x0[1]); w.y = cvt_pk_bf16(x0[2], x0[3]); w.z = cvt_pk_bf16(x1[0], x1[1]); w.w = cvt_pk_bf16(x1[2], x1[3]);
;                         *(u32x4*)(xb + off) = w; } }
.LBB0_271:
	v_add_u32_e32 v48, 0x90, v140
	s_waitcnt lgkmcnt(0)
	v_ashrrev_i32_e32 v49, 31, v48
	v_lshlrev_b64 v[50:51], 11, v[48:49]
	v_lshl_add_u64 v[52:53], v[50:51], 0, v[138:139]
	v_lshl_add_u64 v[54:55], v[52:53], 1, s[12:13]
	s_and_b64 vcc, exec, s[44:45]
	v_lshlrev_b32_e32 v50, 16, v220
	v_and_b32_e32 v51, 0xffff0000, v220
	v_lshlrev_b32_e32 v56, 16, v221
	v_and_b32_e32 v57, 0xffff0000, v221
	v_lshlrev_b32_e32 v60, 16, v222
	v_and_b32_e32 v61, 0xffff0000, v222
	v_lshlrev_b32_e32 v58, 16, v223
	v_and_b32_e32 v59, 0xffff0000, v223
	v_pk_fma_f32 v[46:47], s[10:11], v[46:47], v[56:57]
	v_pk_fma_f32 v[44:45], s[76:77], v[44:45], v[50:51]
	v_pk_fma_f32 v[42:43], s[10:11], v[42:43], v[58:59]
	v_pk_fma_f32 v[40:41], s[76:77], v[40:41], v[60:61]
	v_lshl_add_u64 v[50:51], v[52:53], 2, s[28:29]
	s_cbranch_vccnz .LBB0_314
	global_store_dwordx4 v[50:51], v[44:47], off
	global_store_dwordx4 v[50:51], v[40:43], off offset:16
	s_cbranch_execnz .LBB0_274

; __device__ __forceinline__ unsigned cvt_pk_bf16(float lo, float hi) { unsigned r; asm volatile("v_cvt_pk_bf16_f32 %0, %1, %2" : "=v"(r) : "v"(lo), "v"(hi)); return r; }
;     __device__ __forceinline__ void operator()(const f32x4 (&acc)[2][2][4][2], const Unit& u, int wr, int wc, int fr, int fq) const {
;     ...
;                 for (int bj = 0; bj < 2; ++bj) { const size_t off = (size_t)row * 2048 + col0 + bj * HALF;
;                     f32x4 b0, b1;
;                     if (base32) { b0 = *(const f32x4*)(base32 + off); b1 = *(const f32x4*)(base32 + off + 4); }
;                     else { const u32x4 bw = *(const u32x4*)(xb + off);
;                         b0 = (f32x4){__uint_as_float(bw.x << 16), __uint_as_float(bw.x & 0xffff0000u), __uint_as_float(bw.y << 16), __uint_as_float(bw.y & 0xffff0000u)};
;                         b1 = (f32x4){__uint_as_float(bw.z << 16), __uint_as_float(bw.z & 0xffff0000u), __uint_as_float(bw.w << 16), __uint_as_float(bw.w & 0xffff0000u)}; }
;                     const f32x4 x0 = b0 + acc[ai][bj][m][0] * alpha, x1 = b1 + acc[ai][bj][m][1] * alpha;
;                     q += (x0[0] * x0[0] + x0[1] * x0[1]) + (x0[2] * x0[2] + x0[3] * x0[3]) + (x1[0] * x1[0] + x1[1] * x1[1]) + (x1[2] * x1[2] + x1[3] * x1[3]);
;                     if (out32) { *(f32x4*)(out32 + off) = x0; *(f32x4*)(out32 + off + 4) = x1; }
;                     else { u32x4 w; w.x = cvt_pk_bf16(x0[0], x0[1]); w.y = cvt_pk_bf16(x0[2], x0[3]); w.z = cvt_pk_bf16(x1[0], x1[1]); w.w = cvt_pk_bf16(x1[2], x1[3]);
;                         *(u32x4*)(xb + off) = w; } }
.LBB0_274:
	v_lshlrev_b64 v[52:53], 1, v[52:53]
	v_or_b32_e32 v52, 0x100, v52
	v_lshl_add_u64 v[52:53], s[12:13], 0, v[52:53]
	s_and_b64 vcc, exec, s[44:45]
	v_lshlrev_b32_e32 v58, 16, v224
	v_and_b32_e32 v59, 0xffff0000, v224
	v_lshlrev_b32_e32 v54, 16, v225
	v_and_b32_e32 v55, 0xffff0000, v225
	v_lshlrev_b32_e32 v60, 16, v226
	v_and_b32_e32 v61, 0xffff0000, v226
	v_lshlrev_b32_e32 v56, 16, v227
	v_and_b32_e32 v57, 0xffff0000, v227
	v_pk_fma_f32 v[38:39], s[10:11], v[38:39], v[54:55]
	v_pk_fma_f32 v[36:37], s[76:77], v[36:37], v[58:59]
	v_pk_fma_f32 v[34:35], s[10:11], v[34:35], v[56:57]
	v_pk_fma_f32 v[32:33], s[76:77], v[32:33], v[60:61]
	s_cbranch_vccnz .LBB0_315
	global_store_dwordx4 v[50:51], v[36:39], off offset:512
	global_store_dwordx4 v[50:51], v[32:35], off offset:528
	s_cbranch_execnz .LBB0_277

; __device__ __forceinline__ unsigned cvt_pk_bf16(float lo, float hi) { unsigned r; asm volatile("v_cvt_pk_bf16_f32 %0, %1, %2" : "=v"(r) : "v"(lo), "v"(hi)); return r; }
;     __device__ __forceinline__ void operator()(const f32x4 (&acc)[2][2][4][2], const Unit& u, int wr, int wc, int fr, int fq) const {
;     ...
;                 for (int bj = 0; bj < 2; ++bj) { const size_t off = (size_t)row * 2048 + col0 + bj * HALF;
;                     f32x4 b0, b1;
;                     if (base32) { b0 = *(const f32x4*)(base32 + off); b1 = *(const f32x4*)(base32 + off + 4); }
;                     else { const u32x4 bw = *(const u32x4*)(xb + off);
;                         b0 = (f32x4){__uint_as_float(bw.x << 16), __uint_as_float(bw.x & 0xffff0000u), __uint_as_float(bw.y << 16), __uint_as_float(bw.y & 0xffff0000u)};
;                         b1 = (f32x4){__uint_as_float(bw.z << 16), __uint_as_float(bw.z & 0xffff0000u), __uint_as_float(bw.w << 16), __uint_as_float(bw.w & 0xffff0000u)}; }
;                     const f32x4 x0 = b0 + acc[ai][bj][m][0] * alpha, x1 = b1 + acc[ai][bj][m][1] * alpha;
;                     q += (x0[0] * x0[0] + x0[1] * x0[1]) + (x0[2] * x0[2] + x0[3] * x0[3]) + (x1[0] * x1[0] + x1[1] * x1[1]) + (x1[2] * x1[2] + x1[3] * x1[3]);
;                     if (out32) { *(f32x4*)(out32 + off) = x0; *(f32x4*)(out32 + off + 4) = x1; }
;                     else { u32x4 w; w.x = cvt_pk_bf16(x0[0], x0[1]); w.y = cvt_pk_bf16(x0[2], x0[3]); w.z = cvt_pk_bf16(x1[0], x1[1]); w.w = cvt_pk_bf16(x1[2], x1[3]);
;                         *(u32x4*)(xb + off) = w; } }
.LBB0_281:
	v_add_u32_e32 v32, 0xa0, v140
	s_waitcnt lgkmcnt(0)
	v_ashrrev_i32_e32 v33, 31, v32
	v_lshlrev_b64 v[34:35], 11, v[32:33]
	v_lshl_add_u64 v[36:37], v[34:35], 0, v[138:139]
	v_lshl_add_u64 v[38:39], v[36:37], 1, s[12:13]
	s_and_b64 vcc, exec, s[44:45]
	v_lshlrev_b32_e32 v34, 16, v228
	v_and_b32_e32 v35, 0xffff0000, v228
	v_lshlrev_b32_e32 v40, 16, v229
	v_and_b32_e32 v41, 0xffff0000, v229
	v_lshlrev_b32_e32 v44, 16, v230
	v_and_b32_e32 v45, 0xffff0000, v230
	v_lshlrev_b32_e32 v42, 16, v231
	v_and_b32_e32 v43, 0xffff0000, v231
	v_pk_fma_f32 v[30:31], s[10:11], v[30:31], v[40:41]
	v_pk_fma_f32 v[28:29], s[76:77], v[28:29], v[34:35]
	v_pk_fma_f32 v[26:27], s[10:11], v[26:27], v[42:43]
	v_pk_fma_f32 v[24:25], s[76:77], v[24:25], v[44:45]
	v_lshl_add_u64 v[34:35], v[36:37], 2, s[28:29]
	s_cbranch_vccnz .LBB0_316
	global_store_dwordx4 v[34:35], v[28:31], off
	global_store_dwordx4 v[34:35], v[24:27], off offset:16
	s_cbranch_execnz .LBB0_284

; __device__ __forceinline__ unsigned cvt_pk_bf16(float lo, float hi) { unsigned r; asm volatile("v_cvt_pk_bf16_f32 %0, %1, %2" : "=v"(r) : "v"(lo), "v"(hi)); return r; }
;     __device__ __forceinline__ void operator()(const f32x4 (&acc)[2][2][4][2], const Unit& u, int wr, int wc, int fr, int fq) const {
;     ...
;                 for (int bj = 0; bj < 2; ++bj) { const size_t off = (size_t)row * 2048 + col0 + bj * HALF;
;                     f32x4 b0, b1;
;                     if (base32) { b0 = *(const f32x4*)(base32 + off); b1 = *(const f32x4*)(base32 + off + 4); }
;                     else { const u32x4 bw = *(const u32x4*)(xb + off);
;                         b0 = (f32x4){__uint_as_float(bw.x << 16), __uint_as_float(bw.x & 0xffff0000u), __uint_as_float(bw.y << 16), __uint_as_float(bw.y & 0xffff0000u)};
;                         b1 = (f32x4){__uint_as_float(bw.z << 16), __uint_as_float(bw.z & 0xffff0000u), __uint_as_float(bw.w << 16), __uint_as_float(bw.w & 0xffff0000u)}; }
;                     const f32x4 x0 = b0 + acc[ai][bj][m][0] * alpha, x1 = b1 + acc[ai][bj][m][1] * alpha;
;                     q += (x0[0] * x0[0] + x0[1] * x0[1]) + (x0[2] * x0[2] + x0[3] * x0[3]) + (x1[0] * x1[0] + x1[1] * x1[1]) + (x1[2] * x1[2] + x1[3] * x1[3]);
;                     if (out32) { *(f32x4*)(out32 + off) = x0; *(f32x4*)(out32 + off + 4) = x1; }
;                     else { u32x4 w; w.x = cvt_pk_bf16(x0[0], x0[1]); w.y = cvt_pk_bf16(x0[2], x0[3]); w.z = cvt_pk_bf16(x1[0], x1[1]); w.w = cvt_pk_bf16(x1[2], x1[3]);
;                         *(u32x4*)(xb + off) = w; } }
.LBB0_284:
	v_lshlrev_b64 v[36:37], 1, v[36:37]
	v_or_b32_e32 v36, 0x100, v36
	v_lshl_add_u64 v[36:37], s[12:13], 0, v[36:37]
	s_and_b64 vcc, exec, s[44:45]
	v_lshlrev_b32_e32 v42, 16, v232
	v_and_b32_e32 v43, 0xffff0000, v232
	v_lshlrev_b32_e32 v38, 16, v233
	v_and_b32_e32 v39, 0xffff0000, v233
	v_lshlrev_b32_e32 v44, 16, v234
	v_and_b32_e32 v45, 0xffff0000, v234
	v_lshlrev_b32_e32 v40, 16, v235
	v_and_b32_e32 v41, 0xffff0000, v235
	v_pk_fma_f32 v[22:23], s[10:11], v[22:23], v[38:39]
	v_pk_fma_f32 v[20:21], s[76:77], v[20:21], v[42:43]
	v_pk_fma_f32 v[18:19], s[10:11], v[18:19], v[40:41]
	v_pk_fma_f32 v[16:17], s[76:77], v[16:17], v[44:45]
	s_cbranch_vccnz .LBB0_317
	global_store_dwordx4 v[34:35], v[20:23], off offset:512
	global_store_dwordx4 v[34:35], v[16:19], off offset:528
	s_cbranch_execnz .LBB0_287

; __device__ __forceinline__ unsigned cvt_pk_bf16(float lo, float hi) { unsigned r; asm volatile("v_cvt_pk_bf16_f32 %0, %1, %2" : "=v"(r) : "v"(lo), "v"(hi)); return r; }
;     __device__ __forceinline__ void operator()(const f32x4 (&acc)[2][2][4][2], const Unit& u, int wr, int wc, int fr, int fq) const {
;     ...
;                 for (int bj = 0; bj < 2; ++bj) { const size_t off = (size_t)row * 2048 + col0 + bj * HALF;
;                     f32x4 b0, b1;
;                     if (base32) { b0 = *(const f32x4*)(base32 + off); b1 = *(const f32x4*)(base32 + off + 4); }
;                     else { const u32x4 bw = *(const u32x4*)(xb + off);
;                         b0 = (f32x4){__uint_as_float(bw.x << 16), __uint_as_float(bw.x & 0xffff0000u), __uint_as_float(bw.y << 16), __uint_as_float(bw.y & 0xffff0000u)};
;                         b1 = (f32x4){__uint_as_float(bw.z << 16), __uint_as_float(bw.z & 0xffff0000u), __uint_as_float(bw.w << 16), __uint_as_float(bw.w & 0xffff0000u)}; }
;                     const f32x4 x0 = b0 + acc[ai][bj][m][0] * alpha, x1 = b1 + acc[ai][bj][m][1] * alpha;
;                     q += (x0[0] * x0[0] + x0[1] * x0[1]) + (x0[2] * x0[2] + x0[3] * x0[3]) + (x1[0] * x1[0] + x1[1] * x1[1]) + (x1[2] * x1[2] + x1[3] * x1[3]);
;                     if (out32) { *(f32x4*)(out32 + off) = x0; *(f32x4*)(out32 + off + 4) = x1; }
;                     else { u32x4 w; w.x = cvt_pk_bf16(x0[0], x0[1]); w.y = cvt_pk_bf16(x0[2], x0[3]); w.z = cvt_pk_bf16(x1[0], x1[1]); w.w = cvt_pk_bf16(x1[2], x1[3]);
;                         *(u32x4*)(xb + off) = w; } }
.LBB0_291:
	v_add_u32_e32 v16, 0xb0, v140
	s_waitcnt lgkmcnt(0)
	v_ashrrev_i32_e32 v17, 31, v16
	v_lshlrev_b64 v[18:19], 11, v[16:17]
	v_lshl_add_u64 v[20:21], v[18:19], 0, v[138:139]
	v_lshl_add_u64 v[22:23], v[20:21], 1, s[12:13]
	s_and_b64 vcc, exec, s[44:45]
	v_lshlrev_b32_e32 v18, 16, v240
	v_and_b32_e32 v19, 0xffff0000, v240
	v_lshlrev_b32_e32 v24, 16, v241
	v_and_b32_e32 v25, 0xffff0000, v241
	v_lshlrev_b32_e32 v28, 16, v242
	v_and_b32_e32 v29, 0xffff0000, v242
	v_lshlrev_b32_e32 v26, 16, v243
	v_and_b32_e32 v27, 0xffff0000, v243
	v_pk_fma_f32 v[14:15], s[10:11], v[14:15], v[24:25]
	v_pk_fma_f32 v[12:13], s[76:77], v[12:13], v[18:19]
	v_pk_fma_f32 v[10:11], s[10:11], v[10:11], v[26:27]
	v_pk_fma_f32 v[8:9], s[76:77], v[8:9], v[28:29]
	v_lshl_add_u64 v[18:19], v[20:21], 2, s[28:29]
	s_cbranch_vccnz .LBB0_318
	global_store_dwordx4 v[18:19], v[12:15], off
	global_store_dwordx4 v[18:19], v[8:11], off offset:16
	s_cbranch_execnz .LBB0_294

; __device__ __forceinline__ unsigned cvt_pk_bf16(float lo, float hi) { unsigned r; asm volatile("v_cvt_pk_bf16_f32 %0, %1, %2" : "=v"(r) : "v"(lo), "v"(hi)); return r; }
;     __device__ __forceinline__ void operator()(const f32x4 (&acc)[2][2][4][2], const Unit& u, int wr, int wc, int fr, int fq) const {
;     ...
;                 for (int bj = 0; bj < 2; ++bj) { const size_t off = (size_t)row * 2048 + col0 + bj * HALF;
;                     f32x4 b0, b1;
;                     if (base32) { b0 = *(const f32x4*)(base32 + off); b1 = *(const f32x4*)(base32 + off + 4); }
;                     else { const u32x4 bw = *(const u32x4*)(xb + off);
;                         b0 = (f32x4){__uint_as_float(bw.x << 16), __uint_as_float(bw.x & 0xffff0000u), __uint_as_float(bw.y << 16), __uint_as_float(bw.y & 0xffff0000u)};
;                         b1 = (f32x4){__uint_as_float(bw.z << 16), __uint_as_float(bw.z & 0xffff0000u), __uint_as_float(bw.w << 16), __uint_as_float(bw.w & 0xffff0000u)}; }
;                     const f32x4 x0 = b0 + acc[ai][bj][m][0] * alpha, x1 = b1 + acc[ai][bj][m][1] * alpha;
;                     q += (x0[0] * x0[0] + x0[1] * x0[1]) + (x0[2] * x0[2] + x0[3] * x0[3]) + (x1[0] * x1[0] + x1[1] * x1[1]) + (x1[2] * x1[2] + x1[3] * x1[3]);
;                     if (out32) { *(f32x4*)(out32 + off) = x0; *(f32x4*)(out32 + off + 4) = x1; }
;                     else { u32x4 w; w.x = cvt_pk_bf16(x0[0], x0[1]); w.y = cvt_pk_bf16(x0[2], x0[3]); w.z = cvt_pk_bf16(x1[0], x1[1]); w.w = cvt_pk_bf16(x1[2], x1[3]);
;                         *(u32x4*)(xb + off) = w; } }
.LBB0_294:
	v_lshlrev_b64 v[20:21], 1, v[20:21]
	v_or_b32_e32 v20, 0x100, v20
	v_lshl_add_u64 v[20:21], s[12:13], 0, v[20:21]
	s_and_b64 vcc, exec, s[44:45]
	v_lshlrev_b32_e32 v26, 16, v244
	v_and_b32_e32 v27, 0xffff0000, v244
	v_lshlrev_b32_e32 v22, 16, v245
	v_and_b32_e32 v23, 0xffff0000, v245
	v_lshlrev_b32_e32 v28, 16, v246
	v_and_b32_e32 v29, 0xffff0000, v246
	v_lshlrev_b32_e32 v24, 16, v247
	v_and_b32_e32 v25, 0xffff0000, v247
	v_pk_fma_f32 v[6:7], s[10:11], v[6:7], v[22:23]
	v_pk_fma_f32 v[4:5], s[76:77], v[4:5], v[26:27]
	v_pk_fma_f32 v[2:3], s[10:11], v[2:3], v[24:25]
	v_pk_fma_f32 v[0:1], s[76:77], v[0:1], v[28:29]
	s_cbranch_vccnz .LBB0_319
	global_store_dwordx4 v[18:19], v[4:7], off offset:512
	global_store_dwordx4 v[18:19], v[0:3], off offset:528
	s_cbranch_execnz .LBB0_297
